# P1/P8 epilogue start: eight row-scale LDS reads in one batch, sums by plain adds (was two batches with register shuffles), stacked on v85
# speedup vs baseline: 1.0028x; 1.0009x over previous
.LBB0_208:
	s_add_u32 s4, s46, 0xfffffe00
	s_addc_u32 s5, s47, -1
	s_add_i32 s2, s76, s3
	v_lshl_add_u32 v140, v141, 4, s2
	ds_read_b128 v[152:155], v140
	ds_read_b128 v[156:159], v140 offset:256
	ds_read_b128 v[160:163], v140 offset:512
	ds_read_b128 v[164:167], v140 offset:768
	ds_read_b128 v[174:177], v140 offset:2048
	ds_read_b128 v[178:181], v140 offset:2304
	ds_read_b128 v[182:185], v140 offset:2560
	ds_read_b128 v[188:191], v140 offset:2816
	s_lshl_b32 s2, s10, 8
	s_waitcnt lgkmcnt(0)
	s_waitcnt lgkmcnt(0)
	v_add_f32_e32 v152, v153, v152
	v_add_f32_e32 v154, v154, v155
	v_add_f32_e32 v152, v152, v154
	v_fmamk_f32 v152, v152, 0x3a800000, v148
	v_rsq_f32_e32 v170, v152
	v_add_f32_e32 v156, v157, v156
	v_add_f32_e32 v158, v158, v159
	v_add_f32_e32 v156, v156, v158
	v_fmamk_f32 v156, v156, 0x3a800000, v148
	v_rsq_f32_e32 v171, v156
	v_add_f32_e32 v160, v161, v160
	v_add_f32_e32 v162, v162, v163
	v_add_f32_e32 v160, v160, v162
	v_fmamk_f32 v160, v160, 0x3a800000, v148
	v_rsq_f32_e32 v172, v160
	v_add_f32_e32 v164, v165, v164
	v_add_f32_e32 v166, v166, v167
	v_add_f32_e32 v164, v164, v166
	v_fmamk_f32 v164, v164, 0x3a800000, v148
	v_rsq_f32_e32 v173, v164
	v_add_f32_e32 v174, v175, v174
	v_add_f32_e32 v176, v176, v177
	v_add_f32_e32 v174, v174, v176
	v_fmamk_f32 v174, v174, 0x3a800000, v148
	v_rsq_f32_e32 v168, v174
	v_add_f32_e32 v178, v179, v178
	v_add_f32_e32 v180, v180, v181
	v_add_f32_e32 v178, v178, v180
	v_fmamk_f32 v178, v178, 0x3a800000, v148
	v_rsq_f32_e32 v169, v178
	v_add_f32_e32 v182, v183, v182
	v_add_f32_e32 v184, v184, v185
	v_add_f32_e32 v182, v182, v184
	v_fmamk_f32 v182, v182, 0x3a800000, v148
	v_rsq_f32_e32 v149, v182
	v_add_f32_e32 v188, v189, v188
	v_add_f32_e32 v190, v190, v191
	v_add_f32_e32 v140, v188, v190
	s_add_i32 s2, s2, s59
	v_mul_f32_e32 v153, 0xbfb8aa3b, v170
	v_pk_mul_f32 v[154:155], v[118:119], v[152:153] op_sel:[0,1]
	v_pk_mul_f32 v[156:157], v[114:115], v[152:153] op_sel:[0,1]
	v_pk_mul_f32 v[158:159], v[120:121], v[152:153] op_sel:[0,1]
	v_pk_mul_f32 v[160:161], v[116:117], v[152:153] op_sel:[0,1]
	v_exp_f32_e32 v154, v154
	v_exp_f32_e32 v155, v155
	v_exp_f32_e32 v156, v156
	v_exp_f32_e32 v157, v157
	v_exp_f32_e32 v158, v158
	v_exp_f32_e32 v159, v159
	v_exp_f32_e32 v160, v160
	v_exp_f32_e32 v161, v161
	v_pk_add_f32 v[154:155], v[154:155], 1.0 op_sel_hi:[1,0]
	v_pk_add_f32 v[156:157], v[156:157], 1.0 op_sel_hi:[1,0]
	v_pk_add_f32 v[158:159], v[158:159], 1.0 op_sel_hi:[1,0]
	v_pk_add_f32 v[160:161], v[160:161], 1.0 op_sel_hi:[1,0]
	v_rcp_f32_e32 v154, v154
	v_rcp_f32_e32 v155, v155
	v_rcp_f32_e32 v156, v156
	v_rcp_f32_e32 v157, v157
	v_rcp_f32_e32 v158, v158
	v_rcp_f32_e32 v159, v159
	v_rcp_f32_e32 v160, v160
	v_rcp_f32_e32 v161, v161
	s_nop 0
	v_add_u32_e32 v141, s2, v141
	s_lshl_b32 s2, s60, 7
	s_or_b32 s2, s2, s61
	v_mul_f32_e32 v152, v170, v170
	v_lshl_add_u32 v150, v150, 3, s2
	v_pk_mul_f32 v[120:121], v[120:121], v[128:129]
	v_pk_mul_f32 v[118:119], v[118:119], v[126:127]
	v_pk_mul_f32 v[126:127], v[152:153], v[154:155] op_sel_hi:[0,1]
	v_pk_mul_f32 v[128:129], v[152:153], v[158:159] op_sel_hi:[0,1]
	v_pk_mul_f32 v[114:115], v[114:115], v[122:123]
	v_pk_mul_f32 v[122:123], v[152:153], v[156:157] op_sel_hi:[0,1]
	v_readlane_b32 s2, v255, 0
	v_pk_mul_f32 v[120:121], v[120:121], v[128:129]
	v_pk_mul_f32 v[118:119], v[118:119], v[126:127]
	v_pk_mul_f32 v[116:117], v[116:117], v[124:125]
	v_pk_mul_f32 v[124:125], v[152:153], v[160:161] op_sel_hi:[0,1]
	v_pk_mul_f32 v[114:115], v[114:115], v[122:123]
	v_readlane_b32 s3, v255, 1
	s_waitcnt lgkmcnt(0)
	v_ashrrev_i32_e32 v151, 31, v150
	v_pk_mul_f32 v[116:117], v[116:117], v[124:125]
	v_cvt_pk_bf16_f32 v118, v118, v119
	v_cvt_pk_bf16_f32 v119, v120, v121
	v_cvt_pk_bf16_f32 v120, v114, v115
	v_mov_b64_e32 v[114:115], s[2:3]
	v_cvt_pk_bf16_f32 v121, v116, v117
	v_mad_i64_i32 v[122:123], s[2:3], v141, s50, v[114:115]
	v_lshlrev_b64 v[116:117], 1, v[150:151]
	v_lshl_add_u64 v[116:117], v[122:123], 0, v[116:117]
	s_cmp_eq_u32 s98, 1
	s_cbranch_scc1 .Lwt_0
	global_store_dwordx4 v[116:117], v[118:121], off
	s_branch .Lwtd_0

.LBB0_1725:
	s_add_u32 s4, s50, 0xfffffe00
	s_addc_u32 s5, s51, -1
	s_add_i32 s3, s88, s12
	v_lshl_add_u32 v140, v141, 4, s3
	ds_read_b128 v[152:155], v140
	ds_read_b128 v[156:159], v140 offset:256
	ds_read_b128 v[160:163], v140 offset:512
	ds_read_b128 v[164:167], v140 offset:768
	ds_read_b128 v[174:177], v140 offset:2048
	ds_read_b128 v[178:181], v140 offset:2304
	ds_read_b128 v[182:185], v140 offset:2560
	ds_read_b128 v[188:191], v140 offset:2816
	s_lshl_b32 s3, s10, 8
	s_waitcnt lgkmcnt(0)
	s_waitcnt lgkmcnt(0)
	v_add_f32_e32 v152, v153, v152
	v_add_f32_e32 v154, v154, v155
	v_add_f32_e32 v152, v152, v154
	v_fmamk_f32 v152, v152, 0x3a800000, v148
	v_rsq_f32_e32 v170, v152
	v_add_f32_e32 v156, v157, v156
	v_add_f32_e32 v158, v158, v159
	v_add_f32_e32 v156, v156, v158
	v_fmamk_f32 v156, v156, 0x3a800000, v148
	v_rsq_f32_e32 v171, v156
	v_add_f32_e32 v160, v161, v160
	v_add_f32_e32 v162, v162, v163
	v_add_f32_e32 v160, v160, v162
	v_fmamk_f32 v160, v160, 0x3a800000, v148
	v_rsq_f32_e32 v172, v160
	v_add_f32_e32 v164, v165, v164
	v_add_f32_e32 v166, v166, v167
	v_add_f32_e32 v164, v164, v166
	v_fmamk_f32 v164, v164, 0x3a800000, v148
	v_rsq_f32_e32 v173, v164
	v_add_f32_e32 v174, v175, v174
	v_add_f32_e32 v176, v176, v177
	v_add_f32_e32 v174, v174, v176
	v_fmamk_f32 v174, v174, 0x3a800000, v148
	v_rsq_f32_e32 v168, v174
	v_add_f32_e32 v178, v179, v178
	v_add_f32_e32 v180, v180, v181
	v_add_f32_e32 v178, v178, v180
	v_fmamk_f32 v178, v178, 0x3a800000, v148
	v_rsq_f32_e32 v169, v178
	v_add_f32_e32 v182, v183, v182
	v_add_f32_e32 v184, v184, v185
	v_add_f32_e32 v182, v182, v184
	v_fmamk_f32 v182, v182, 0x3a800000, v148
	v_rsq_f32_e32 v149, v182
	v_add_f32_e32 v188, v189, v188
	v_add_f32_e32 v190, v190, v191
	v_add_f32_e32 v140, v188, v190
	v_mul_f32_e32 v153, 0xbfb8aa3b, v170
	v_pk_mul_f32 v[154:155], v[118:119], v[152:153] op_sel:[0,1]
	v_pk_mul_f32 v[156:157], v[114:115], v[152:153] op_sel:[0,1]
	v_pk_mul_f32 v[158:159], v[120:121], v[152:153] op_sel:[0,1]
	v_pk_mul_f32 v[160:161], v[116:117], v[152:153] op_sel:[0,1]
	v_exp_f32_e32 v154, v154
	v_exp_f32_e32 v155, v155
	v_exp_f32_e32 v156, v156
	v_exp_f32_e32 v157, v157
	v_exp_f32_e32 v158, v158
	v_exp_f32_e32 v159, v159
	v_exp_f32_e32 v160, v160
	v_exp_f32_e32 v161, v161
	v_pk_add_f32 v[154:155], v[154:155], 1.0 op_sel_hi:[1,0]
	v_pk_add_f32 v[156:157], v[156:157], 1.0 op_sel_hi:[1,0]
	v_pk_add_f32 v[158:159], v[158:159], 1.0 op_sel_hi:[1,0]
	v_pk_add_f32 v[160:161], v[160:161], 1.0 op_sel_hi:[1,0]
	v_rcp_f32_e32 v154, v154
	v_rcp_f32_e32 v155, v155
	v_rcp_f32_e32 v156, v156
	v_rcp_f32_e32 v157, v157
	v_rcp_f32_e32 v158, v158
	v_rcp_f32_e32 v159, v159
	v_rcp_f32_e32 v160, v160
	v_rcp_f32_e32 v161, v161
	s_nop 0
	s_add_i32 s3, s3, s82
	v_add_u32_e32 v141, s3, v141
	s_lshl_b32 s3, s83, 7
	v_mul_f32_e32 v152, v170, v170
	s_or_b32 s3, s3, s84
	v_pk_mul_f32 v[120:121], v[120:121], v[128:129]
	v_pk_mul_f32 v[118:119], v[118:119], v[126:127]
	v_pk_mul_f32 v[126:127], v[152:153], v[154:155] op_sel_hi:[0,1]
	v_pk_mul_f32 v[128:129], v[152:153], v[158:159] op_sel_hi:[0,1]
	v_pk_mul_f32 v[114:115], v[114:115], v[122:123]
	v_pk_mul_f32 v[122:123], v[152:153], v[156:157] op_sel_hi:[0,1]
	v_readlane_b32 s12, v255, 0
	v_lshl_add_u32 v150, v150, 3, s3
	v_pk_mul_f32 v[120:121], v[120:121], v[128:129]
	v_pk_mul_f32 v[118:119], v[118:119], v[126:127]
	v_pk_mul_f32 v[116:117], v[116:117], v[124:125]
	v_pk_mul_f32 v[124:125], v[152:153], v[160:161] op_sel_hi:[0,1]
	v_pk_mul_f32 v[114:115], v[114:115], v[122:123]
	v_readlane_b32 s13, v255, 1
	s_waitcnt lgkmcnt(0)
	v_ashrrev_i32_e32 v151, 31, v150
	v_pk_mul_f32 v[116:117], v[116:117], v[124:125]
	v_cvt_pk_bf16_f32 v118, v118, v119
	v_cvt_pk_bf16_f32 v119, v120, v121
	v_cvt_pk_bf16_f32 v120, v114, v115
	v_mov_b64_e32 v[114:115], s[12:13]
	v_cvt_pk_bf16_f32 v121, v116, v117
	v_mad_i64_i32 v[122:123], s[12:13], v141, s91, v[114:115]
	v_lshlrev_b64 v[116:117], 1, v[150:151]
	v_lshl_add_u64 v[116:117], v[122:123], 0, v[116:117]
	s_cmp_eq_u32 s98, 1
	s_cbranch_scc1 .Lwt_8
	global_store_dwordx4 v[116:117], v[118:121], off
	s_branch .Lwtd_8
